# differential attention: O1 - lambda*O2 combine and per-head RMS norm fused into the second map's unit epilogue (second map taken from the LDS staging image, lambda computed once before the unit loop);
# speedup vs baseline: 1.0369x; 1.0046x over previous
.LBB0_1077:
	v_and_b32_e32 v0, 63, v206
	v_and_b32_e32 v186, 31, v206
	v_bfe_u32 v3, v206, 5, 1
	v_mul_u32_u24_e32 v2, 0xc00, v0
	v_lshlrev_b32_e32 v0, 3, v206
	v_and_b32_e32 v4, 24, v0
	v_mul_u32_u24_e32 v0, 0xc00, v186
	v_lshlrev_b32_e32 v188, 3, v3
	v_or_b32_e32 v6, v188, v0
	v_lshlrev_b32_e32 v0, 10, v3
	v_lshlrev_b32_e32 v5, 4, v186
	v_add3_u32 v189, 0, v0, v5
	v_lshlrev_b32_e32 v0, 1, v206
	v_lshlrev_b32_e32 v191, 2, v3
	v_bfe_u32 v5, v206, 2, 2
	v_and_b32_e32 v0, 32, v0
	v_or_b32_e32 v5, v191, v5
	v_add_u32_e32 v0, 0, v0
	v_lshlrev_b32_e32 v5, 6, v5
	s_cmpk_lg_i32 s30, 0x100
	v_add3_u32 v192, v0, v4, v5
	v_and_b32_e32 v0, 3, v206
	s_cselect_b64 s[0:1], -1, 0
	s_and_b32 s34, s31, 15
	v_mov_b32_e32 v1, 0
	v_lshlrev_b32_e32 v0, 4, v0
	s_ashr_i32 s33, s31, 4
	s_xor_b32 s35, s34, 31
	v_and_b32_e32 v3, 15, v206
	v_lshl_add_u64 v[10:11], s[74:75], 0, v[0:1]
	s_mov_b64 s[6:7], 0x5321000
	s_add_u32 s36, s74, 0x5201000
	v_bfe_u32 v190, v206, 4, 2
	v_lshlrev_b32_e32 v8, 3, v3
	v_lshl_add_u64 v[168:169], v[10:11], 0, s[6:7]
	s_mov_b64 s[6:7], 0x52c1000
	s_addc_u32 s37, s75, 0
	v_bfe_u32 v187, v206, 2, 4
	v_mul_u32_u24_e32 v193, 0x110, v186
	v_lshlrev_b32_e32 v194, 4, v3
	v_mul_u32_u24_e32 v195, 0x110, v190
	v_lshl_add_u64 v[170:171], v[10:11], 0, s[6:7]
	v_lshlrev_b32_e32 v172, 1, v2
	s_mov_b64 s[8:9], 0x800
	v_lshlrev_b32_e32 v174, 1, v4
	s_mov_b64 s[10:11], 0x80
	s_mov_b64 s[12:13], 0x60800
	s_mov_b64 s[14:15], 0x60000
	s_mov_b64 s[16:17], 0x60080
	v_lshlrev_b32_e32 v196, 1, v6
	s_mov_b64 s[18:19], 0xc0000
	s_mov_b64 s[20:21], 0xc0080
	s_mov_b64 s[22:23], 0x120000
	s_mov_b32 s38, 0x41000000
	s_movk_i32 s39, 0x400
	v_lshlrev_b32_e32 v176, 1, v8
	v_mov_b32_e32 v197, 0x60000
	v_mov_b32_e32 v198, 0xff800000
	s_mov_b32 s40, 0
	v_and_b32_e32 v0, 63, v206
	v_lshlrev_b32_e32 v0, 2, v0
	global_load_dword v2, v0, s[56:57]
	global_load_dword v3, v0, s[58:59]
	global_load_dword v4, v0, s[60:61]
	global_load_dword v5, v0, s[62:63]
	v_mbcnt_hi_u32_b32 v0, -1, v207
	v_xor_b32_e32 v6, 1, v0
	v_xor_b32_e32 v7, 2, v0
	v_xor_b32_e32 v8, 4, v0
	v_xor_b32_e32 v9, 8, v0
	v_xor_b32_e32 v10, 16, v0
	v_xor_b32_e32 v11, 32, v0
	v_lshlrev_b32_e32 v6, 2, v6
	v_lshlrev_b32_e32 v7, 2, v7
	v_lshlrev_b32_e32 v8, 2, v8
	v_lshlrev_b32_e32 v9, 2, v9
	v_lshlrev_b32_e32 v10, 2, v10
	v_lshlrev_b32_e32 v11, 2, v11
	s_waitcnt vmcnt(0)
	v_mul_f32_e32 v12, v2, v3
	v_mul_f32_e32 v13, v4, v5
	ds_bpermute_b32 v12, v6, v12
	ds_bpermute_b32 v13, v6, v13
	s_waitcnt lgkmcnt(0)
	v_fmac_f32_e32 v12, v2, v3
	v_fmac_f32_e32 v13, v4, v5
	ds_bpermute_b32 v2, v7, v12
	ds_bpermute_b32 v3, v7, v13
	s_waitcnt lgkmcnt(0)
	v_add_f32_e32 v12, v12, v2
	v_add_f32_e32 v13, v13, v3
	ds_bpermute_b32 v2, v8, v12
	ds_bpermute_b32 v3, v8, v13
	s_waitcnt lgkmcnt(0)
	v_add_f32_e32 v12, v12, v2
	v_add_f32_e32 v13, v13, v3
	ds_bpermute_b32 v2, v9, v12
	ds_bpermute_b32 v3, v9, v13
	s_waitcnt lgkmcnt(0)
	v_add_f32_e32 v12, v12, v2
	v_add_f32_e32 v13, v13, v3
	ds_bpermute_b32 v2, v10, v12
	ds_bpermute_b32 v3, v10, v13
	s_waitcnt lgkmcnt(0)
	v_add_f32_e32 v12, v12, v2
	v_add_f32_e32 v13, v13, v3
	ds_bpermute_b32 v2, v11, v12
	ds_bpermute_b32 v3, v11, v13
	s_waitcnt lgkmcnt(0)
	v_add_f32_e32 v12, v12, v2
	v_add_f32_e32 v13, v13, v3
	v_mul_f32_e32 v12, 0x3fb8aa3b, v12
	v_mul_f32_e32 v13, 0x3fb8aa3b, v13
	v_exp_f32_e32 v12, v12
	v_exp_f32_e32 v13, v13
	s_nop 0
	v_sub_f32_e32 v236, v12, v13
	v_add_f32_e32 v236, 0x3eb60549, v236
	v_mov_b32_e32 v237, v236
	s_branch .LBB0_1080
.Ldat_fuse:
	s_add_u32 s98, s84, s51
	s_addc_u32 s99, s85, 0
	s_lshl_b32 s100, s43, 11
	s_lshr_b32 s101, s43, 21
	s_lshl_b32 s5, s44, 11
	s_or_b32 s101, s101, s5
	s_add_u32 s98, s98, s100
	s_addc_u32 s99, s99, s101
	s_mov_b64 s[100:101], 0x2000
	v_add3_u32 v18, s25, v194, v195
	v_mov_b32_e32 v177, v1
	v_lshl_add_u64 v[100:101], s[98:99], 0, v[176:177]
	v_lshlrev_b32_e32 v0, 11, v190
	v_lshl_add_u64 v[100:101], v[100:101], 0, v[0:1]
	v_lshl_add_u64 v[102:103], v[100:101], 0, s[100:101]
	v_lshl_add_u64 v[104:105], v[102:103], 0, s[100:101]
	v_lshl_add_u64 v[106:107], v[104:105], 0, s[100:101]
	v_lshl_add_u64 v[108:109], v[106:107], 0, s[100:101]
	v_lshl_add_u64 v[110:111], v[108:109], 0, s[100:101]
	v_lshl_add_u64 v[112:113], v[110:111], 0, s[100:101]
	v_lshl_add_u64 v[114:115], v[112:113], 0, s[100:101]
	s_nop 0
	global_load_dwordx4 v[20:23], v[100:101], off
	global_load_dwordx4 v[24:27], v[102:103], off
	global_load_dwordx4 v[28:31], v[104:105], off
	global_load_dwordx4 v[32:35], v[106:107], off
	global_load_dwordx4 v[36:39], v[108:109], off
	global_load_dwordx4 v[40:43], v[110:111], off
	global_load_dwordx4 v[44:47], v[112:113], off
	global_load_dwordx4 v[48:51], v[114:115], off
	s_waitcnt lgkmcnt(0)
	ds_read_b128 v[52:55], v18
	ds_read_b128 v[56:59], v18 offset:1088
	ds_read_b128 v[60:63], v18 offset:2176
	ds_read_b128 v[64:67], v18 offset:3264
	ds_read_b128 v[68:71], v18 offset:4352
	ds_read_b128 v[72:75], v18 offset:5440
	ds_read_b128 v[76:79], v18 offset:6528
	ds_read_b128 v[80:83], v18 offset:7616
	v_mov_b32_e32 v84, 0x358637bd
	s_waitcnt vmcnt(7) lgkmcnt(7)
	v_lshlrev_b32_e32 v10, 16, v20
	v_and_b32_e32 v11, 0xffff0000, v20
	v_lshlrev_b32_e32 v12, 16, v52
	v_and_b32_e32 v13, 0xffff0000, v52
	v_pk_fma_f32 v[2:3], v[236:237], v[12:13], v[10:11] neg_lo:[1,0,0] neg_hi:[1,0,0]
	v_lshlrev_b32_e32 v10, 16, v21
	v_and_b32_e32 v11, 0xffff0000, v21
	v_lshlrev_b32_e32 v12, 16, v53
	v_and_b32_e32 v13, 0xffff0000, v53
	v_pk_fma_f32 v[4:5], v[236:237], v[12:13], v[10:11] neg_lo:[1,0,0] neg_hi:[1,0,0]
	v_lshlrev_b32_e32 v10, 16, v22
	v_and_b32_e32 v11, 0xffff0000, v22
	v_lshlrev_b32_e32 v12, 16, v54
	v_and_b32_e32 v13, 0xffff0000, v54
	v_pk_fma_f32 v[6:7], v[236:237], v[12:13], v[10:11] neg_lo:[1,0,0] neg_hi:[1,0,0]
	v_lshlrev_b32_e32 v10, 16, v23
	v_and_b32_e32 v11, 0xffff0000, v23
	v_lshlrev_b32_e32 v12, 16, v55
	v_and_b32_e32 v13, 0xffff0000, v55
	v_pk_fma_f32 v[8:9], v[236:237], v[12:13], v[10:11] neg_lo:[1,0,0] neg_hi:[1,0,0]
	v_pk_mul_f32 v[14:15], v[2:3], v[2:3]
	v_pk_fma_f32 v[14:15], v[4:5], v[4:5], v[14:15]
	v_pk_fma_f32 v[14:15], v[6:7], v[6:7], v[14:15]
	v_pk_fma_f32 v[14:15], v[8:9], v[8:9], v[14:15]
	s_nop 0
	v_add_f32_e32 v14, v14, v15
	s_nop 1
	v_add_f32_dpp v14, v14, v14 row_ror:8 row_mask:0xf bank_mask:0xf
	s_nop 1
	v_add_f32_dpp v14, v14, v14 row_ror:4 row_mask:0xf bank_mask:0xf
	s_nop 1
	v_add_f32_dpp v14, v14, v14 row_ror:2 row_mask:0xf bank_mask:0xf
	s_nop 1
	v_add_f32_dpp v14, v14, v14 row_ror:1 row_mask:0xf bank_mask:0xf
	v_fmamk_f32 v14, v14, 0x3c000000, v84
	v_rsq_f32_e32 v14, v14
	s_nop 0
	v_pk_mul_f32 v[2:3], v[2:3], v[14:15] op_sel_hi:[1,0]
	v_pk_mul_f32 v[4:5], v[4:5], v[14:15] op_sel_hi:[1,0]
	v_pk_mul_f32 v[6:7], v[6:7], v[14:15] op_sel_hi:[1,0]
	v_pk_mul_f32 v[8:9], v[8:9], v[14:15] op_sel_hi:[1,0]
	v_cvt_pk_bf16_f32 v10, v2, v3
	v_cvt_pk_bf16_f32 v11, v4, v5
	v_cvt_pk_bf16_f32 v12, v6, v7
	v_cvt_pk_bf16_f32 v13, v8, v9
	global_store_dwordx4 v[100:101], v[10:13], off
	s_nop 1
	s_waitcnt vmcnt(7) lgkmcnt(6)
	v_lshlrev_b32_e32 v10, 16, v24
	v_and_b32_e32 v11, 0xffff0000, v24
	v_lshlrev_b32_e32 v12, 16, v56
	v_and_b32_e32 v13, 0xffff0000, v56
	v_pk_fma_f32 v[2:3], v[236:237], v[12:13], v[10:11] neg_lo:[1,0,0] neg_hi:[1,0,0]
	v_lshlrev_b32_e32 v10, 16, v25
	v_and_b32_e32 v11, 0xffff0000, v25
	v_lshlrev_b32_e32 v12, 16, v57
	v_and_b32_e32 v13, 0xffff0000, v57
	v_pk_fma_f32 v[4:5], v[236:237], v[12:13], v[10:11] neg_lo:[1,0,0] neg_hi:[1,0,0]
	v_lshlrev_b32_e32 v10, 16, v26
	v_and_b32_e32 v11, 0xffff0000, v26
	v_lshlrev_b32_e32 v12, 16, v58
	v_and_b32_e32 v13, 0xffff0000, v58
	v_pk_fma_f32 v[6:7], v[236:237], v[12:13], v[10:11] neg_lo:[1,0,0] neg_hi:[1,0,0]
	v_lshlrev_b32_e32 v10, 16, v27
	v_and_b32_e32 v11, 0xffff0000, v27
	v_lshlrev_b32_e32 v12, 16, v59
	v_and_b32_e32 v13, 0xffff0000, v59
	v_pk_fma_f32 v[8:9], v[236:237], v[12:13], v[10:11] neg_lo:[1,0,0] neg_hi:[1,0,0]
	v_pk_mul_f32 v[14:15], v[2:3], v[2:3]
	v_pk_fma_f32 v[14:15], v[4:5], v[4:5], v[14:15]
	v_pk_fma_f32 v[14:15], v[6:7], v[6:7], v[14:15]
	v_pk_fma_f32 v[14:15], v[8:9], v[8:9], v[14:15]
	s_nop 0
	v_add_f32_e32 v14, v14, v15
	s_nop 1
	v_add_f32_dpp v14, v14, v14 row_ror:8 row_mask:0xf bank_mask:0xf
	s_nop 1
	v_add_f32_dpp v14, v14, v14 row_ror:4 row_mask:0xf bank_mask:0xf
	s_nop 1
	v_add_f32_dpp v14, v14, v14 row_ror:2 row_mask:0xf bank_mask:0xf
	s_nop 1
	v_add_f32_dpp v14, v14, v14 row_ror:1 row_mask:0xf bank_mask:0xf
	v_fmamk_f32 v14, v14, 0x3c000000, v84
	v_rsq_f32_e32 v14, v14
	s_nop 0
	v_pk_mul_f32 v[2:3], v[2:3], v[14:15] op_sel_hi:[1,0]
	v_pk_mul_f32 v[4:5], v[4:5], v[14:15] op_sel_hi:[1,0]
	v_pk_mul_f32 v[6:7], v[6:7], v[14:15] op_sel_hi:[1,0]
	v_pk_mul_f32 v[8:9], v[8:9], v[14:15] op_sel_hi:[1,0]
	v_cvt_pk_bf16_f32 v10, v2, v3
	v_cvt_pk_bf16_f32 v11, v4, v5
	v_cvt_pk_bf16_f32 v12, v6, v7
	v_cvt_pk_bf16_f32 v13, v8, v9
	global_store_dwordx4 v[102:103], v[10:13], off
	s_nop 1
	s_waitcnt vmcnt(7) lgkmcnt(5)
	v_lshlrev_b32_e32 v10, 16, v28
	v_and_b32_e32 v11, 0xffff0000, v28
	v_lshlrev_b32_e32 v12, 16, v60
	v_and_b32_e32 v13, 0xffff0000, v60
	v_pk_fma_f32 v[2:3], v[236:237], v[12:13], v[10:11] neg_lo:[1,0,0] neg_hi:[1,0,0]
	v_lshlrev_b32_e32 v10, 16, v29
	v_and_b32_e32 v11, 0xffff0000, v29
	v_lshlrev_b32_e32 v12, 16, v61
	v_and_b32_e32 v13, 0xffff0000, v61
	v_pk_fma_f32 v[4:5], v[236:237], v[12:13], v[10:11] neg_lo:[1,0,0] neg_hi:[1,0,0]
	v_lshlrev_b32_e32 v10, 16, v30
	v_and_b32_e32 v11, 0xffff0000, v30
	v_lshlrev_b32_e32 v12, 16, v62
	v_and_b32_e32 v13, 0xffff0000, v62
	v_pk_fma_f32 v[6:7], v[236:237], v[12:13], v[10:11] neg_lo:[1,0,0] neg_hi:[1,0,0]
	v_lshlrev_b32_e32 v10, 16, v31
	v_and_b32_e32 v11, 0xffff0000, v31
	v_lshlrev_b32_e32 v12, 16, v63
	v_and_b32_e32 v13, 0xffff0000, v63
	v_pk_fma_f32 v[8:9], v[236:237], v[12:13], v[10:11] neg_lo:[1,0,0] neg_hi:[1,0,0]
	v_pk_mul_f32 v[14:15], v[2:3], v[2:3]
	v_pk_fma_f32 v[14:15], v[4:5], v[4:5], v[14:15]
	v_pk_fma_f32 v[14:15], v[6:7], v[6:7], v[14:15]
	v_pk_fma_f32 v[14:15], v[8:9], v[8:9], v[14:15]
	s_nop 0
	v_add_f32_e32 v14, v14, v15
	s_nop 1
	v_add_f32_dpp v14, v14, v14 row_ror:8 row_mask:0xf bank_mask:0xf
	s_nop 1
	v_add_f32_dpp v14, v14, v14 row_ror:4 row_mask:0xf bank_mask:0xf
	s_nop 1
	v_add_f32_dpp v14, v14, v14 row_ror:2 row_mask:0xf bank_mask:0xf
	s_nop 1
	v_add_f32_dpp v14, v14, v14 row_ror:1 row_mask:0xf bank_mask:0xf
	v_fmamk_f32 v14, v14, 0x3c000000, v84
	v_rsq_f32_e32 v14, v14
	s_nop 0
	v_pk_mul_f32 v[2:3], v[2:3], v[14:15] op_sel_hi:[1,0]
	v_pk_mul_f32 v[4:5], v[4:5], v[14:15] op_sel_hi:[1,0]
	v_pk_mul_f32 v[6:7], v[6:7], v[14:15] op_sel_hi:[1,0]
	v_pk_mul_f32 v[8:9], v[8:9], v[14:15] op_sel_hi:[1,0]
	v_cvt_pk_bf16_f32 v10, v2, v3
	v_cvt_pk_bf16_f32 v11, v4, v5
	v_cvt_pk_bf16_f32 v12, v6, v7
	v_cvt_pk_bf16_f32 v13, v8, v9
	global_store_dwordx4 v[104:105], v[10:13], off
	s_nop 1
	s_waitcnt vmcnt(7) lgkmcnt(4)
	v_lshlrev_b32_e32 v10, 16, v32
	v_and_b32_e32 v11, 0xffff0000, v32
	v_lshlrev_b32_e32 v12, 16, v64
	v_and_b32_e32 v13, 0xffff0000, v64
	v_pk_fma_f32 v[2:3], v[236:237], v[12:13], v[10:11] neg_lo:[1,0,0] neg_hi:[1,0,0]
	v_lshlrev_b32_e32 v10, 16, v33
	v_and_b32_e32 v11, 0xffff0000, v33
	v_lshlrev_b32_e32 v12, 16, v65
	v_and_b32_e32 v13, 0xffff0000, v65
	v_pk_fma_f32 v[4:5], v[236:237], v[12:13], v[10:11] neg_lo:[1,0,0] neg_hi:[1,0,0]
	v_lshlrev_b32_e32 v10, 16, v34
	v_and_b32_e32 v11, 0xffff0000, v34
	v_lshlrev_b32_e32 v12, 16, v66
	v_and_b32_e32 v13, 0xffff0000, v66
	v_pk_fma_f32 v[6:7], v[236:237], v[12:13], v[10:11] neg_lo:[1,0,0] neg_hi:[1,0,0]
	v_lshlrev_b32_e32 v10, 16, v35
	v_and_b32_e32 v11, 0xffff0000, v35
	v_lshlrev_b32_e32 v12, 16, v67
	v_and_b32_e32 v13, 0xffff0000, v67
	v_pk_fma_f32 v[8:9], v[236:237], v[12:13], v[10:11] neg_lo:[1,0,0] neg_hi:[1,0,0]
	v_pk_mul_f32 v[14:15], v[2:3], v[2:3]
	v_pk_fma_f32 v[14:15], v[4:5], v[4:5], v[14:15]
	v_pk_fma_f32 v[14:15], v[6:7], v[6:7], v[14:15]
	v_pk_fma_f32 v[14:15], v[8:9], v[8:9], v[14:15]
	s_nop 0
	v_add_f32_e32 v14, v14, v15
	s_nop 1
	v_add_f32_dpp v14, v14, v14 row_ror:8 row_mask:0xf bank_mask:0xf
	s_nop 1
	v_add_f32_dpp v14, v14, v14 row_ror:4 row_mask:0xf bank_mask:0xf
	s_nop 1
	v_add_f32_dpp v14, v14, v14 row_ror:2 row_mask:0xf bank_mask:0xf
	s_nop 1
	v_add_f32_dpp v14, v14, v14 row_ror:1 row_mask:0xf bank_mask:0xf
	v_fmamk_f32 v14, v14, 0x3c000000, v84
	v_rsq_f32_e32 v14, v14
	s_nop 0
	v_pk_mul_f32 v[2:3], v[2:3], v[14:15] op_sel_hi:[1,0]
	v_pk_mul_f32 v[4:5], v[4:5], v[14:15] op_sel_hi:[1,0]
	v_pk_mul_f32 v[6:7], v[6:7], v[14:15] op_sel_hi:[1,0]
	v_pk_mul_f32 v[8:9], v[8:9], v[14:15] op_sel_hi:[1,0]
	v_cvt_pk_bf16_f32 v10, v2, v3
	v_cvt_pk_bf16_f32 v11, v4, v5
	v_cvt_pk_bf16_f32 v12, v6, v7
	v_cvt_pk_bf16_f32 v13, v8, v9
	global_store_dwordx4 v[106:107], v[10:13], off
	s_nop 1
	s_waitcnt vmcnt(7) lgkmcnt(3)
	v_lshlrev_b32_e32 v10, 16, v36
	v_and_b32_e32 v11, 0xffff0000, v36
	v_lshlrev_b32_e32 v12, 16, v68
	v_and_b32_e32 v13, 0xffff0000, v68
	v_pk_fma_f32 v[2:3], v[236:237], v[12:13], v[10:11] neg_lo:[1,0,0] neg_hi:[1,0,0]
	v_lshlrev_b32_e32 v10, 16, v37
	v_and_b32_e32 v11, 0xffff0000, v37
	v_lshlrev_b32_e32 v12, 16, v69
	v_and_b32_e32 v13, 0xffff0000, v69
	v_pk_fma_f32 v[4:5], v[236:237], v[12:13], v[10:11] neg_lo:[1,0,0] neg_hi:[1,0,0]
	v_lshlrev_b32_e32 v10, 16, v38
	v_and_b32_e32 v11, 0xffff0000, v38
	v_lshlrev_b32_e32 v12, 16, v70
	v_and_b32_e32 v13, 0xffff0000, v70
	v_pk_fma_f32 v[6:7], v[236:237], v[12:13], v[10:11] neg_lo:[1,0,0] neg_hi:[1,0,0]
	v_lshlrev_b32_e32 v10, 16, v39
	v_and_b32_e32 v11, 0xffff0000, v39
	v_lshlrev_b32_e32 v12, 16, v71
	v_and_b32_e32 v13, 0xffff0000, v71
	v_pk_fma_f32 v[8:9], v[236:237], v[12:13], v[10:11] neg_lo:[1,0,0] neg_hi:[1,0,0]
	v_pk_mul_f32 v[14:15], v[2:3], v[2:3]
	v_pk_fma_f32 v[14:15], v[4:5], v[4:5], v[14:15]
	v_pk_fma_f32 v[14:15], v[6:7], v[6:7], v[14:15]
	v_pk_fma_f32 v[14:15], v[8:9], v[8:9], v[14:15]
	s_nop 0
	v_add_f32_e32 v14, v14, v15
	s_nop 1
	v_add_f32_dpp v14, v14, v14 row_ror:8 row_mask:0xf bank_mask:0xf
	s_nop 1
	v_add_f32_dpp v14, v14, v14 row_ror:4 row_mask:0xf bank_mask:0xf
	s_nop 1
	v_add_f32_dpp v14, v14, v14 row_ror:2 row_mask:0xf bank_mask:0xf
	s_nop 1
	v_add_f32_dpp v14, v14, v14 row_ror:1 row_mask:0xf bank_mask:0xf
	v_fmamk_f32 v14, v14, 0x3c000000, v84
	v_rsq_f32_e32 v14, v14
	s_nop 0
	v_pk_mul_f32 v[2:3], v[2:3], v[14:15] op_sel_hi:[1,0]
	v_pk_mul_f32 v[4:5], v[4:5], v[14:15] op_sel_hi:[1,0]
	v_pk_mul_f32 v[6:7], v[6:7], v[14:15] op_sel_hi:[1,0]
	v_pk_mul_f32 v[8:9], v[8:9], v[14:15] op_sel_hi:[1,0]
	v_cvt_pk_bf16_f32 v10, v2, v3
	v_cvt_pk_bf16_f32 v11, v4, v5
	v_cvt_pk_bf16_f32 v12, v6, v7
	v_cvt_pk_bf16_f32 v13, v8, v9
	global_store_dwordx4 v[108:109], v[10:13], off
	s_nop 1
	s_waitcnt vmcnt(7) lgkmcnt(2)
	v_lshlrev_b32_e32 v10, 16, v40
	v_and_b32_e32 v11, 0xffff0000, v40
	v_lshlrev_b32_e32 v12, 16, v72
	v_and_b32_e32 v13, 0xffff0000, v72
	v_pk_fma_f32 v[2:3], v[236:237], v[12:13], v[10:11] neg_lo:[1,0,0] neg_hi:[1,0,0]
	v_lshlrev_b32_e32 v10, 16, v41
	v_and_b32_e32 v11, 0xffff0000, v41
	v_lshlrev_b32_e32 v12, 16, v73
	v_and_b32_e32 v13, 0xffff0000, v73
	v_pk_fma_f32 v[4:5], v[236:237], v[12:13], v[10:11] neg_lo:[1,0,0] neg_hi:[1,0,0]
	v_lshlrev_b32_e32 v10, 16, v42
	v_and_b32_e32 v11, 0xffff0000, v42
	v_lshlrev_b32_e32 v12, 16, v74
	v_and_b32_e32 v13, 0xffff0000, v74
	v_pk_fma_f32 v[6:7], v[236:237], v[12:13], v[10:11] neg_lo:[1,0,0] neg_hi:[1,0,0]
	v_lshlrev_b32_e32 v10, 16, v43
	v_and_b32_e32 v11, 0xffff0000, v43
	v_lshlrev_b32_e32 v12, 16, v75
	v_and_b32_e32 v13, 0xffff0000, v75
	v_pk_fma_f32 v[8:9], v[236:237], v[12:13], v[10:11] neg_lo:[1,0,0] neg_hi:[1,0,0]
	v_pk_mul_f32 v[14:15], v[2:3], v[2:3]
	v_pk_fma_f32 v[14:15], v[4:5], v[4:5], v[14:15]
	v_pk_fma_f32 v[14:15], v[6:7], v[6:7], v[14:15]
	v_pk_fma_f32 v[14:15], v[8:9], v[8:9], v[14:15]
	s_nop 0
	v_add_f32_e32 v14, v14, v15
	s_nop 1
	v_add_f32_dpp v14, v14, v14 row_ror:8 row_mask:0xf bank_mask:0xf
	s_nop 1
	v_add_f32_dpp v14, v14, v14 row_ror:4 row_mask:0xf bank_mask:0xf
	s_nop 1
	v_add_f32_dpp v14, v14, v14 row_ror:2 row_mask:0xf bank_mask:0xf
	s_nop 1
	v_add_f32_dpp v14, v14, v14 row_ror:1 row_mask:0xf bank_mask:0xf
	v_fmamk_f32 v14, v14, 0x3c000000, v84
	v_rsq_f32_e32 v14, v14
	s_nop 0
	v_pk_mul_f32 v[2:3], v[2:3], v[14:15] op_sel_hi:[1,0]
	v_pk_mul_f32 v[4:5], v[4:5], v[14:15] op_sel_hi:[1,0]
	v_pk_mul_f32 v[6:7], v[6:7], v[14:15] op_sel_hi:[1,0]
	v_pk_mul_f32 v[8:9], v[8:9], v[14:15] op_sel_hi:[1,0]
	v_cvt_pk_bf16_f32 v10, v2, v3
	v_cvt_pk_bf16_f32 v11, v4, v5
	v_cvt_pk_bf16_f32 v12, v6, v7
	v_cvt_pk_bf16_f32 v13, v8, v9
	global_store_dwordx4 v[110:111], v[10:13], off
	s_nop 1
	s_waitcnt vmcnt(7) lgkmcnt(1)
	v_lshlrev_b32_e32 v10, 16, v44
	v_and_b32_e32 v11, 0xffff0000, v44
	v_lshlrev_b32_e32 v12, 16, v76
	v_and_b32_e32 v13, 0xffff0000, v76
	v_pk_fma_f32 v[2:3], v[236:237], v[12:13], v[10:11] neg_lo:[1,0,0] neg_hi:[1,0,0]
	v_lshlrev_b32_e32 v10, 16, v45
	v_and_b32_e32 v11, 0xffff0000, v45
	v_lshlrev_b32_e32 v12, 16, v77
	v_and_b32_e32 v13, 0xffff0000, v77
	v_pk_fma_f32 v[4:5], v[236:237], v[12:13], v[10:11] neg_lo:[1,0,0] neg_hi:[1,0,0]
	v_lshlrev_b32_e32 v10, 16, v46
	v_and_b32_e32 v11, 0xffff0000, v46
	v_lshlrev_b32_e32 v12, 16, v78
	v_and_b32_e32 v13, 0xffff0000, v78
	v_pk_fma_f32 v[6:7], v[236:237], v[12:13], v[10:11] neg_lo:[1,0,0] neg_hi:[1,0,0]
	v_lshlrev_b32_e32 v10, 16, v47
	v_and_b32_e32 v11, 0xffff0000, v47
	v_lshlrev_b32_e32 v12, 16, v79
	v_and_b32_e32 v13, 0xffff0000, v79
	v_pk_fma_f32 v[8:9], v[236:237], v[12:13], v[10:11] neg_lo:[1,0,0] neg_hi:[1,0,0]
	v_pk_mul_f32 v[14:15], v[2:3], v[2:3]
	v_pk_fma_f32 v[14:15], v[4:5], v[4:5], v[14:15]
	v_pk_fma_f32 v[14:15], v[6:7], v[6:7], v[14:15]
	v_pk_fma_f32 v[14:15], v[8:9], v[8:9], v[14:15]
	s_nop 0
	v_add_f32_e32 v14, v14, v15
	s_nop 1
	v_add_f32_dpp v14, v14, v14 row_ror:8 row_mask:0xf bank_mask:0xf
	s_nop 1
	v_add_f32_dpp v14, v14, v14 row_ror:4 row_mask:0xf bank_mask:0xf
	s_nop 1
	v_add_f32_dpp v14, v14, v14 row_ror:2 row_mask:0xf bank_mask:0xf
	s_nop 1
	v_add_f32_dpp v14, v14, v14 row_ror:1 row_mask:0xf bank_mask:0xf
	v_fmamk_f32 v14, v14, 0x3c000000, v84
	v_rsq_f32_e32 v14, v14
	s_nop 0
	v_pk_mul_f32 v[2:3], v[2:3], v[14:15] op_sel_hi:[1,0]
	v_pk_mul_f32 v[4:5], v[4:5], v[14:15] op_sel_hi:[1,0]
	v_pk_mul_f32 v[6:7], v[6:7], v[14:15] op_sel_hi:[1,0]
	v_pk_mul_f32 v[8:9], v[8:9], v[14:15] op_sel_hi:[1,0]
	v_cvt_pk_bf16_f32 v10, v2, v3
	v_cvt_pk_bf16_f32 v11, v4, v5
	v_cvt_pk_bf16_f32 v12, v6, v7
	v_cvt_pk_bf16_f32 v13, v8, v9
	global_store_dwordx4 v[112:113], v[10:13], off
	s_nop 1
	s_waitcnt vmcnt(7) lgkmcnt(0)
	v_lshlrev_b32_e32 v10, 16, v48
	v_and_b32_e32 v11, 0xffff0000, v48
	v_lshlrev_b32_e32 v12, 16, v80
	v_and_b32_e32 v13, 0xffff0000, v80
	v_pk_fma_f32 v[2:3], v[236:237], v[12:13], v[10:11] neg_lo:[1,0,0] neg_hi:[1,0,0]
	v_lshlrev_b32_e32 v10, 16, v49
	v_and_b32_e32 v11, 0xffff0000, v49
	v_lshlrev_b32_e32 v12, 16, v81
	v_and_b32_e32 v13, 0xffff0000, v81
	v_pk_fma_f32 v[4:5], v[236:237], v[12:13], v[10:11] neg_lo:[1,0,0] neg_hi:[1,0,0]
	v_lshlrev_b32_e32 v10, 16, v50
	v_and_b32_e32 v11, 0xffff0000, v50
	v_lshlrev_b32_e32 v12, 16, v82
	v_and_b32_e32 v13, 0xffff0000, v82
	v_pk_fma_f32 v[6:7], v[236:237], v[12:13], v[10:11] neg_lo:[1,0,0] neg_hi:[1,0,0]
	v_lshlrev_b32_e32 v10, 16, v51
	v_and_b32_e32 v11, 0xffff0000, v51
	v_lshlrev_b32_e32 v12, 16, v83
	v_and_b32_e32 v13, 0xffff0000, v83
	v_pk_fma_f32 v[8:9], v[236:237], v[12:13], v[10:11] neg_lo:[1,0,0] neg_hi:[1,0,0]
	v_pk_mul_f32 v[14:15], v[2:3], v[2:3]
	v_pk_fma_f32 v[14:15], v[4:5], v[4:5], v[14:15]
	v_pk_fma_f32 v[14:15], v[6:7], v[6:7], v[14:15]
	v_pk_fma_f32 v[14:15], v[8:9], v[8:9], v[14:15]
	s_nop 0
	v_add_f32_e32 v14, v14, v15
	s_nop 1
	v_add_f32_dpp v14, v14, v14 row_ror:8 row_mask:0xf bank_mask:0xf
	s_nop 1
	v_add_f32_dpp v14, v14, v14 row_ror:4 row_mask:0xf bank_mask:0xf
	s_nop 1
	v_add_f32_dpp v14, v14, v14 row_ror:2 row_mask:0xf bank_mask:0xf
	s_nop 1
	v_add_f32_dpp v14, v14, v14 row_ror:1 row_mask:0xf bank_mask:0xf
	v_fmamk_f32 v14, v14, 0x3c000000, v84
	v_rsq_f32_e32 v14, v14
	s_nop 0
	v_pk_mul_f32 v[2:3], v[2:3], v[14:15] op_sel_hi:[1,0]
	v_pk_mul_f32 v[4:5], v[4:5], v[14:15] op_sel_hi:[1,0]
	v_pk_mul_f32 v[6:7], v[6:7], v[14:15] op_sel_hi:[1,0]
	v_pk_mul_f32 v[8:9], v[8:9], v[14:15] op_sel_hi:[1,0]
	v_cvt_pk_bf16_f32 v10, v2, v3
	v_cvt_pk_bf16_f32 v11, v4, v5
	v_cvt_pk_bf16_f32 v12, v6, v7
	v_cvt_pk_bf16_f32 v13, v8, v9
	global_store_dwordx4 v[114:115], v[10:13], off
	s_nop 1
	s_add_i32 s40, s40, 1
	s_mov_b64 s[6:7], 0
	s_branch .Ldat_fuse_join
.LBB0_1078:
	v_mov_b32_e32 v0, v173
	s_nop 1
	v_permlane32_swap_b32_e32 v173, v0
	v_add_f32_e32 v0, v173, v0
	v_rcp_f32_e32 v0, v0
	s_cmp_eq_u32 s49, 0
	s_cselect_b64 s[6:7], -1, 0
	s_add_u32 s3, s84, s51
	s_addc_u32 s5, s85, 0
	s_and_b64 s[6:7], s[6:7], exec
	s_mulk_i32 s48, 0x2200
	v_pk_mul_f32 v[2:3], v[52:53], v[0:1] op_sel_hi:[1,0]
	v_pk_mul_f32 v[52:53], v[54:55], v[0:1] op_sel_hi:[1,0]
	s_cselect_b32 s5, s5, s50
	s_cselect_b32 s24, s3, s45
	s_cselect_b32 s3, s39, 0xc00
	s_add_i32 s25, s48, 0
	v_cvt_pk_bf16_f32 v2, v2, v3
	v_cvt_pk_bf16_f32 v3, v52, v53
	v_pk_mul_f32 v[52:53], v[56:57], v[0:1] op_sel_hi:[1,0]
	v_pk_mul_f32 v[54:55], v[58:59], v[0:1] op_sel_hi:[1,0]
	v_add3_u32 v68, s25, v193, v188
	v_cvt_pk_bf16_f32 v52, v52, v53
	v_cvt_pk_bf16_f32 v53, v54, v55
	s_waitcnt vmcnt(0) lgkmcnt(0)
	s_barrier
	ds_write2_b64 v68, v[2:3], v[52:53] offset1:2
	v_pk_mul_f32 v[2:3], v[60:61], v[0:1] op_sel_hi:[1,0]
	v_pk_mul_f32 v[52:53], v[62:63], v[0:1] op_sel_hi:[1,0]
	v_cvt_pk_bf16_f32 v2, v2, v3
	v_cvt_pk_bf16_f32 v3, v52, v53
	v_pk_mul_f32 v[52:53], v[64:65], v[0:1] op_sel_hi:[1,0]
	v_pk_mul_f32 v[54:55], v[66:67], v[0:1] op_sel_hi:[1,0]
	v_cvt_pk_bf16_f32 v52, v52, v53
	v_cvt_pk_bf16_f32 v53, v54, v55
	ds_write2_b64 v68, v[2:3], v[52:53] offset0:4 offset1:6
	v_pk_mul_f32 v[2:3], v[36:37], v[0:1] op_sel_hi:[1,0]
	v_pk_mul_f32 v[36:37], v[38:39], v[0:1] op_sel_hi:[1,0]
	v_cvt_pk_bf16_f32 v2, v2, v3
	v_cvt_pk_bf16_f32 v3, v36, v37
	v_pk_mul_f32 v[36:37], v[40:41], v[0:1] op_sel_hi:[1,0]
	v_pk_mul_f32 v[38:39], v[42:43], v[0:1] op_sel_hi:[1,0]
	v_cvt_pk_bf16_f32 v36, v36, v37
	v_cvt_pk_bf16_f32 v37, v38, v39
	ds_write2_b64 v68, v[2:3], v[36:37] offset0:8 offset1:10
	v_pk_mul_f32 v[2:3], v[44:45], v[0:1] op_sel_hi:[1,0]
	v_pk_mul_f32 v[36:37], v[46:47], v[0:1] op_sel_hi:[1,0]
	v_cvt_pk_bf16_f32 v2, v2, v3
	v_cvt_pk_bf16_f32 v3, v36, v37
	v_pk_mul_f32 v[36:37], v[48:49], v[0:1] op_sel_hi:[1,0]
	v_pk_mul_f32 v[38:39], v[50:51], v[0:1] op_sel_hi:[1,0]
	v_cvt_pk_bf16_f32 v36, v36, v37
	v_cvt_pk_bf16_f32 v37, v38, v39
	ds_write2_b64 v68, v[2:3], v[36:37] offset0:12 offset1:14
	v_pk_mul_f32 v[2:3], v[20:21], v[0:1] op_sel_hi:[1,0]
	v_pk_mul_f32 v[20:21], v[22:23], v[0:1] op_sel_hi:[1,0]
	v_cvt_pk_bf16_f32 v2, v2, v3
	v_cvt_pk_bf16_f32 v3, v20, v21
	v_pk_mul_f32 v[20:21], v[24:25], v[0:1] op_sel_hi:[1,0]
	v_pk_mul_f32 v[22:23], v[26:27], v[0:1] op_sel_hi:[1,0]
	v_cvt_pk_bf16_f32 v20, v20, v21
	v_cvt_pk_bf16_f32 v21, v22, v23
	ds_write2_b64 v68, v[2:3], v[20:21] offset0:16 offset1:18
	v_pk_mul_f32 v[2:3], v[28:29], v[0:1] op_sel_hi:[1,0]
	v_pk_mul_f32 v[20:21], v[30:31], v[0:1] op_sel_hi:[1,0]
	v_cvt_pk_bf16_f32 v2, v2, v3
	v_cvt_pk_bf16_f32 v3, v20, v21
	v_pk_mul_f32 v[20:21], v[32:33], v[0:1] op_sel_hi:[1,0]
	v_pk_mul_f32 v[22:23], v[34:35], v[0:1] op_sel_hi:[1,0]
	v_cvt_pk_bf16_f32 v20, v20, v21
	v_cvt_pk_bf16_f32 v21, v22, v23
	ds_write2_b64 v68, v[2:3], v[20:21] offset0:20 offset1:22
	v_pk_mul_f32 v[2:3], v[4:5], v[0:1] op_sel_hi:[1,0]
	v_pk_mul_f32 v[4:5], v[6:7], v[0:1] op_sel_hi:[1,0]
	v_cvt_pk_bf16_f32 v2, v2, v3
	v_cvt_pk_bf16_f32 v3, v4, v5
	v_pk_mul_f32 v[4:5], v[8:9], v[0:1] op_sel_hi:[1,0]
	v_pk_mul_f32 v[6:7], v[10:11], v[0:1] op_sel_hi:[1,0]
	v_cvt_pk_bf16_f32 v4, v4, v5
	v_cvt_pk_bf16_f32 v5, v6, v7
	ds_write2_b64 v68, v[2:3], v[4:5] offset0:24 offset1:26
	v_pk_mul_f32 v[2:3], v[12:13], v[0:1] op_sel_hi:[1,0]
	v_pk_mul_f32 v[4:5], v[14:15], v[0:1] op_sel_hi:[1,0]
	v_cvt_pk_bf16_f32 v2, v2, v3
	v_cvt_pk_bf16_f32 v3, v4, v5
	v_pk_mul_f32 v[4:5], v[16:17], v[0:1] op_sel_hi:[1,0]
	v_pk_mul_f32 v[6:7], v[18:19], v[0:1] op_sel_hi:[1,0]
	v_cvt_pk_bf16_f32 v4, v4, v5
	v_cvt_pk_bf16_f32 v5, v6, v7
	ds_write2_b64 v68, v[2:3], v[4:5] offset0:28 offset1:30
	s_cmp_lg_u32 s49, 0
	s_cbranch_scc1 .Ldat_fuse
	s_mul_i32 s44, s44, s3
	s_mul_hi_u32 s6, s43, s3
	s_waitcnt lgkmcnt(0)
	s_add_i32 s7, s6, s44
	s_mul_i32 s6, s43, s3
	v_add3_u32 v18, s25, v194, v195
	s_lshl_b64 s[6:7], s[6:7], 1
	ds_read_b128 v[2:5], v18
	ds_read_b128 v[6:9], v18 offset:1088
	s_add_u32 s6, s24, s6
	s_addc_u32 s7, s5, s7
	v_mov_b32_e32 v177, v1
	v_mul_u32_u24_e32 v0, s3, v190
	v_lshl_add_u64 v[14:15], s[6:7], 0, v[176:177]
	v_lshlrev_b32_e32 v0, 1, v0
	v_lshl_add_u64 v[10:11], v[14:15], 0, v[0:1]
	s_waitcnt lgkmcnt(1)
	global_store_dwordx4 v[10:11], v[2:5], off
	s_lshl_b32 s6, s3, 3
	s_mov_b32 s7, s4
	ds_read_b128 v[2:5], v18 offset:2176
	v_lshl_add_u64 v[16:17], v[10:11], 0, s[6:7]
	ds_read_b128 v[10:13], v18 offset:3264
	s_lshl_b32 s5, s3, 2
	s_waitcnt lgkmcnt(2)
	global_store_dwordx4 v[16:17], v[6:9], off
	s_add_i32 s40, s40, 1
	s_nop 0
	v_lshl_add_u64 v[6:7], v[16:17], 0, s[6:7]
	s_waitcnt lgkmcnt(1)
	global_store_dwordx4 v[6:7], v[2:5], off
	s_nop 1
	v_lshl_add_u64 v[2:3], v[6:7], 0, s[6:7]
	s_add_i32 s6, s5, s5
	s_waitcnt lgkmcnt(0)
	global_store_dwordx4 v[2:3], v[10:13], off
	ds_read_b128 v[2:5], v18 offset:4352
	ds_read_b128 v[6:9], v18 offset:5440
	s_add_i32 s6, s6, s6
	v_mov_b32_e32 v0, s6
	v_mad_u32_u24 v12, s3, v190, v0
	v_lshlrev_b32_e32 v0, 1, v12
	v_add_u32_e32 v12, s5, v12
	v_lshl_add_u64 v[10:11], v[14:15], 0, v[0:1]
	v_lshlrev_b32_e32 v0, 1, v12
	s_waitcnt lgkmcnt(1)
	global_store_dwordx4 v[10:11], v[2:5], off
	v_lshl_add_u64 v[10:11], v[14:15], 0, v[0:1]
	ds_read_b128 v[2:5], v18 offset:6528
	s_waitcnt lgkmcnt(1)
	global_store_dwordx4 v[10:11], v[6:9], off
	ds_read_b128 v[6:9], v18 offset:7616
	v_add_u32_e32 v0, s5, v12
	v_lshl_add_u64 v[10:11], v[0:1], 1, v[14:15]
	v_add_u32_e32 v0, s5, v0
	s_waitcnt lgkmcnt(1)
	global_store_dwordx4 v[10:11], v[2:5], off
	s_mov_b64 s[6:7], 0
	s_nop 0
	v_lshl_add_u64 v[2:3], v[0:1], 1, v[14:15]
	s_waitcnt lgkmcnt(0)
	global_store_dwordx4 v[2:3], v[6:9], off
.Ldat_fuse_join:
	s_waitcnt lgkmcnt(0)
	s_barrier

.LBB0_1135:
	v_mbcnt_hi_u32_b32 v0, -1, v207
	v_xor_b32_e32 v2, 16, v0
	v_xor_b32_e32 v3, 32, v0
	v_lshlrev_b32_e32 v207, 2, v2
	v_lshlrev_b32_e32 v208, 2, v3
	s_nop 0
	s_nop 0
	s_nop 0
	s_nop 0

	.amdhsa_kernel _Z8mega_fwd4Args
		.amdhsa_group_segment_fixed_size 0
		.amdhsa_private_segment_fixed_size 0
		.amdhsa_kernarg_size 400
		.amdhsa_user_sgpr_count 2
		.amdhsa_user_sgpr_dispatch_ptr 0
		.amdhsa_user_sgpr_queue_ptr 0
		.amdhsa_user_sgpr_kernarg_segment_ptr 1
		.amdhsa_user_sgpr_dispatch_id 0
		.amdhsa_user_sgpr_kernarg_preload_length 0
		.amdhsa_user_sgpr_kernarg_preload_offset 0
		.amdhsa_user_sgpr_private_segment_size 0
		.amdhsa_uses_dynamic_stack 0
		.amdhsa_enable_private_segment 0
		.amdhsa_system_sgpr_workgroup_id_x 1
		.amdhsa_system_sgpr_workgroup_id_y 0
		.amdhsa_system_sgpr_workgroup_id_z 0
		.amdhsa_system_sgpr_workgroup_info 0
		.amdhsa_system_vgpr_workitem_id 2
		.amdhsa_next_free_vgpr 239
		.amdhsa_next_free_sgpr 102
		.amdhsa_accum_offset 240
		.amdhsa_reserve_vcc 1
		.amdhsa_float_round_mode_32 0
		.amdhsa_float_round_mode_16_64 0
		.amdhsa_float_denorm_mode_32 3
		.amdhsa_float_denorm_mode_16_64 3
		.amdhsa_dx10_clamp 1
		.amdhsa_ieee_mode 1
		.amdhsa_fp16_overflow 0
		.amdhsa_tg_split 0
		.amdhsa_exception_fp_ieee_invalid_op 0
		.amdhsa_exception_fp_denorm_src 0
		.amdhsa_exception_fp_ieee_div_zero 0
		.amdhsa_exception_fp_ieee_overflow 0
		.amdhsa_exception_fp_ieee_underflow 0
		.amdhsa_exception_fp_ieee_inexact 0
		.amdhsa_exception_int_div_zero 0
	.end_amdhsa_kernel

amdhsa.kernels:
  - .agpr_count:     0
    .args:
      - .offset:         0
        .size:           144
        .value_kind:     by_value
      - .offset:         144
        .size:           4
        .value_kind:     hidden_block_count_x
      - .offset:         148
        .size:           4
        .value_kind:     hidden_block_count_y
      - .offset:         152
        .size:           4
        .value_kind:     hidden_block_count_z
      - .offset:         156
        .size:           2
        .value_kind:     hidden_group_size_x
      - .offset:         158
        .size:           2
        .value_kind:     hidden_group_size_y
      - .offset:         160
        .size:           2
        .value_kind:     hidden_group_size_z
      - .offset:         162
        .size:           2
        .value_kind:     hidden_remainder_x
      - .offset:         164
        .size:           2
        .value_kind:     hidden_remainder_y
      - .offset:         166
        .size:           2
        .value_kind:     hidden_remainder_z
      - .offset:         184
        .size:           8
        .value_kind:     hidden_global_offset_x
      - .offset:         192
        .size:           8
        .value_kind:     hidden_global_offset_y
      - .offset:         200
        .size:           8
        .value_kind:     hidden_global_offset_z
      - .offset:         208
        .size:           2
        .value_kind:     hidden_grid_dims
      - .offset:         232
        .size:           8
        .value_kind:     hidden_multigrid_sync_arg
      - .offset:         264
        .size:           4
        .value_kind:     hidden_dynamic_lds_size
    .group_segment_fixed_size: 0
    .kernarg_segment_align: 8
    .kernarg_segment_size: 400
    .language:       OpenCL C
    .language_version:
      - 2
      - 0
    .max_flat_workgroup_size: 512
    .name:           _Z8mega_fwd4Args
    .private_segment_fixed_size: 0
    .sgpr_count:     108
    .sgpr_spill_count: 8
    .symbol:         _Z8mega_fwd4Args.kd
    .uniform_work_group_size: 1
    .uses_dynamic_stack: false
    .vgpr_count:     239
    .vgpr_spill_count: 0
    .wavefront_size: 64
